# v44 + residual GEMM epilogues: the twelve modulation-vector loads issued together behind one wait (were four serial groups)
# baseline (speedup 1.0000x reference)
; __device__ __forceinline__ unsigned cvt_pk_bf16(float lo, float hi) { unsigned r; asm volatile("v_cvt_pk_bf16_f32 %0, %1, %2" : "=v"(r) : "v"(lo), "v"(hi)); return r; }
; __device__ __forceinline__ float shx(float v, int o, int lane) { return __int_as_float(__builtin_amdgcn_ds_bpermute((lane ^ o) << 2, __float_as_int(v))); }
;     __device__ __forceinline__ void operator()(const f32x4 (&acc)[2][2][4][2], const Unit& u, int wr, int wc, int fr, int fq) const {
;         const int bidx = u.pm >> 4, row0 = u.pm * BM + wr * 64 + fr, col0 = u.pn * BM + wc * 32 + 4 * fq, lane = fq * 16 + fr;
;         f32x4 gv[2][2], gs[2][2];
; #pragma unroll
;         for (int bj = 0; bj < 2; ++bj)
; #pragma unroll
;             for (int n = 0; n < 2; ++n) { const int c = col0 + bj * HALF + n * 16; gv[bj][n] = *(const f32x4*)(gate + (size_t)bidx * NMOD + c);
;                 gs[bj][n] = *(const f32x4*)(gnext + c) * (*(const f32x4*)(scn + (size_t)bidx * NMOD + c) + 1.0f); }
; #pragma unroll
;         for (int ai = 0; ai < 2; ++ai)
; #pragma unroll
;             for (int m = 0; m < 4; ++m) { const int row = row0 + ai * HALF + m * 16; const size_t off = (size_t)row * DM + col0; float ss = 0.f;
; #pragma unroll
;                 for (int bj = 0; bj < 2; ++bj)
; #pragma unroll
;                     for (int n = 0; n < 2; ++n) { const f32x4 x = *(const f32x4*)(src + off + bj * HALF + n * 16) + gv[bj][n] * acc[ai][bj][m][n];
;                         *(f32x4*)(dst + off + bj * HALF + n * 16) = x; ss += (x[0] * x[0] + x[1] * x[1]) + (x[2] * x[2] + x[3] * x[3]);
;                         const f32x4 hh = x * gs[bj][n]; u32x2 w; w.x = cvt_pk_bf16(hh[0], hh[1]); w.y = cvt_pk_bf16(hh[2], hh[3]); *(u32x2*)(Hn + off + bj * HALF + n * 16) = w; }
;                 ss += shx(ss, 16, lane); ss += shx(ss, 32, lane);
;                 if (fq == 0) scr[(ai * HALF + wr * 64 + m * 16 + fr) * 4 + wc] = ss; }
.LBB0_536:
	s_ashr_i32 s25, s34, 4
	s_lshl_b32 s34, s34, 8
	s_mul_hi_i32 s27, s25, 0x6000
	s_mulk_i32 s25, 0x6000
	v_lshl_or_b32 v168, s36, 8, v185
	s_add_u32 s36, s57, s25
	s_addc_u32 s37, s58, s27
	s_add_u32 s38, s59, s25
	v_ashrrev_i32_e32 v169, 31, v168
	s_addc_u32 s39, s60, s27
	v_lshlrev_b64 v[76:77], 2, v[168:169]
	v_lshl_add_u64 v[176:177], s[38:39], 0, v[76:77]
	v_lshl_add_u64 v[170:171], s[36:37], 0, v[76:77]
	v_lshl_add_u64 v[174:175], s[20:21], 0, v[76:77]
	global_load_dwordx4 v[196:199], v[176:177], off
	global_load_dwordx4 v[200:203], v[174:175], off
	global_load_dwordx4 v[204:207], v[170:171], off
	global_load_dwordx4 v[208:211], v[170:171], off offset:64
	global_load_dwordx4 v[212:215], v[174:175], off offset:64
	global_load_dwordx4 v[216:219], v[176:177], off offset:64
	global_load_dwordx4 v[220:223], v[170:171], off offset:512
	global_load_dwordx4 v[224:227], v[174:175], off offset:512
	global_load_dwordx4 v[228:231], v[176:177], off offset:512
	global_load_dwordx4 v[232:235], v[170:171], off offset:576
	global_load_dwordx4 v[236:239], v[174:175], off offset:576
	global_load_dwordx4 v[240:243], v[176:177], off offset:576
	s_waitcnt vmcnt(0)
	v_mov_b32_e32 v76, v196
	v_mov_b32_e32 v77, v197
	v_mov_b32_e32 v78, v198
	v_mov_b32_e32 v79, v199
	v_mov_b32_e32 v72, v200
	v_mov_b32_e32 v73, v201
	v_mov_b32_e32 v74, v202
	v_mov_b32_e32 v75, v203
	v_mov_b32_e32 v88, v204
	v_mov_b32_e32 v89, v205
	v_mov_b32_e32 v90, v206
	v_mov_b32_e32 v91, v207
	v_pk_add_f32 v[78:79], v[78:79], 1.0 op_sel_hi:[1,0]
	v_pk_add_f32 v[76:77], v[76:77], 1.0 op_sel_hi:[1,0]
	v_pk_mul_f32 v[164:165], v[74:75], v[78:79]
	v_pk_mul_f32 v[166:167], v[72:73], v[76:77]
	v_mov_b32_e32 v92, v208
	v_mov_b32_e32 v93, v209
	v_mov_b32_e32 v94, v210
	v_mov_b32_e32 v95, v211
	v_mov_b32_e32 v72, v212
	v_mov_b32_e32 v73, v213
	v_mov_b32_e32 v74, v214
	v_mov_b32_e32 v75, v215
	v_mov_b32_e32 v76, v216
	v_mov_b32_e32 v77, v217
	v_mov_b32_e32 v78, v218
	v_mov_b32_e32 v79, v219
	v_pk_add_f32 v[78:79], v[78:79], 1.0 op_sel_hi:[1,0]
	v_pk_add_f32 v[76:77], v[76:77], 1.0 op_sel_hi:[1,0]
	v_pk_mul_f32 v[160:161], v[74:75], v[78:79]
	v_pk_mul_f32 v[162:163], v[72:73], v[76:77]
	v_mov_b32_e32 v76, v220
	v_mov_b32_e32 v77, v221
	v_mov_b32_e32 v78, v222
	v_mov_b32_e32 v79, v223
	v_mov_b32_e32 v72, v224
	v_mov_b32_e32 v73, v225
	v_mov_b32_e32 v74, v226
	v_mov_b32_e32 v75, v227
	v_mov_b32_e32 v152, v228
	v_mov_b32_e32 v153, v229
	v_mov_b32_e32 v154, v230
	v_mov_b32_e32 v155, v231
	v_pk_add_f32 v[154:155], v[154:155], 1.0 op_sel_hi:[1,0]
	v_pk_add_f32 v[152:153], v[152:153], 1.0 op_sel_hi:[1,0]
	v_pk_mul_f32 v[156:157], v[74:75], v[154:155]
	v_pk_mul_f32 v[158:159], v[72:73], v[152:153]
	v_mov_b32_e32 v72, v232
	v_mov_b32_e32 v73, v233
	v_mov_b32_e32 v74, v234
	v_mov_b32_e32 v75, v235
	v_mov_b32_e32 v152, v236
	v_mov_b32_e32 v153, v237
	v_mov_b32_e32 v154, v238
	v_mov_b32_e32 v155, v239
	s_nop 0
	v_mov_b32_e32 v174, v240
	v_mov_b32_e32 v175, v241
	v_mov_b32_e32 v176, v242
	v_mov_b32_e32 v177, v243
	v_pk_add_f32 v[170:171], v[176:177], 1.0 op_sel_hi:[1,0]
	s_nop 0
	v_pk_mul_f32 v[154:155], v[154:155], v[170:171]
	v_add_u32_e32 v170, s34, v180
	v_pk_add_f32 v[174:175], v[174:175], 1.0 op_sel_hi:[1,0]
	v_ashrrev_i32_e32 v171, 31, v170
	v_pk_mul_f32 v[152:153], v[152:153], v[174:175]
	v_lshlrev_b64 v[174:175], 10, v[170:171]
	v_lshl_add_u64 v[192:193], v[174:175], 0, v[168:169]
	v_lshlrev_b64 v[194:195], 2, v[192:193]
	v_lshl_add_u64 v[178:179], s[4:5], 0, v[194:195]
	v_mov_b32_e32 v228, v194
	v_mov_b32_e32 v229, v228
	global_load_dwordx4 v[196:199], v229, s[4:5]
	global_load_dwordx4 v[200:203], v229, s[4:5] offset:64
	global_load_dwordx4 v[204:207], v229, s[4:5] offset:512
	global_load_dwordx4 v[208:211], v229, s[4:5] offset:576
	v_add_u32_e32 v229, 0x10000, v228
	global_load_dwordx4 v[212:215], v229, s[4:5]
	global_load_dwordx4 v[216:219], v229, s[4:5] offset:64
	global_load_dwordx4 v[220:223], v229, s[4:5] offset:512
	global_load_dwordx4 v[224:227], v229, s[4:5] offset:576
	s_waitcnt vmcnt(7)
	v_pk_fma_f32 v[176:177], v[142:143], v[90:91], v[198:199]
	v_pk_fma_f32 v[174:175], v[140:141], v[88:89], v[196:197]
	v_mul_f32_e32 v143, v177, v177
	v_mul_f32_e32 v142, v175, v175
	v_lshl_add_u64 v[140:141], s[12:13], 0, v[194:195]
	v_fmac_f32_e32 v142, v174, v174
	v_fmac_f32_e32 v143, v176, v176
	global_store_dwordx4 v[140:141], v[174:177], off
	v_add_f32_e32 v194, v142, v143
	v_pk_mul_f32 v[142:143], v[164:165], v[176:177]
	v_pk_mul_f32 v[174:175], v[166:167], v[174:175]
	s_nop 0
	v_cvt_pk_bf16_f32 v174, v174, v175
	v_cvt_pk_bf16_f32 v175, v142, v143
	v_lshl_add_u64 v[142:143], v[192:193], 1, s[18:19]
	global_store_dwordx2 v[142:143], v[174:175], off
	s_waitcnt vmcnt(8)
	v_pk_fma_f32 v[136:137], v[136:137], v[92:93], v[200:201]
	v_pk_fma_f32 v[138:139], v[138:139], v[94:95], v[202:203]
	v_mul_f32_e32 v174, v137, v137
	global_store_dwordx4 v[140:141], v[136:139], off offset:64
	v_fmac_f32_e32 v174, v136, v136
	v_mul_f32_e32 v175, v139, v139
	v_pk_mul_f32 v[136:137], v[162:163], v[136:137]
	v_fmac_f32_e32 v175, v138, v138
	v_pk_mul_f32 v[138:139], v[160:161], v[138:139]
	v_cvt_pk_bf16_f32 v136, v136, v137
	v_add_f32_e32 v174, v174, v175
	v_cvt_pk_bf16_f32 v137, v138, v139
	global_store_dwordx2 v[142:143], v[136:137], off offset:32
	v_add_f32_e32 v174, v194, v174
	s_waitcnt vmcnt(9)
	v_pk_fma_f32 v[132:133], v[132:133], v[76:77], v[204:205]
	v_pk_fma_f32 v[134:135], v[134:135], v[78:79], v[206:207]
	v_mul_f32_e32 v136, v133, v133
	global_store_dwordx4 v[140:141], v[132:135], off offset:512
	v_fmac_f32_e32 v136, v132, v132
	v_mul_f32_e32 v137, v135, v135
	v_pk_mul_f32 v[132:133], v[158:159], v[132:133]
	v_fmac_f32_e32 v137, v134, v134
	v_pk_mul_f32 v[134:135], v[156:157], v[134:135]
	v_cvt_pk_bf16_f32 v132, v132, v133
	v_add_f32_e32 v136, v136, v137
	v_cvt_pk_bf16_f32 v133, v134, v135
	global_store_dwordx2 v[142:143], v[132:133], off offset:256
	v_add_f32_e32 v136, v174, v136
	s_waitcnt vmcnt(10)
	v_pk_fma_f32 v[130:131], v[130:131], v[74:75], v[210:211]
	v_pk_fma_f32 v[128:129], v[128:129], v[72:73], v[208:209]
	v_add_u32_e32 v229, 0x20000, v228
	global_load_dwordx4 v[196:199], v229, s[4:5]
	global_load_dwordx4 v[200:203], v229, s[4:5] offset:64
	global_load_dwordx4 v[204:207], v229, s[4:5] offset:512
	global_load_dwordx4 v[208:211], v229, s[4:5] offset:576
	v_mul_f32_e32 v133, v131, v131
	v_mul_f32_e32 v132, v129, v129
	v_fmac_f32_e32 v132, v128, v128
	v_fmac_f32_e32 v133, v130, v130
	global_store_dwordx4 v[140:141], v[128:131], off offset:576
	v_add_f32_e32 v132, v132, v133
	v_add_f32_e32 v132, v136, v132
	v_pk_mul_f32 v[128:129], v[152:153], v[128:129]
	v_pk_mul_f32 v[130:131], v[154:155], v[130:131]
	v_cvt_pk_bf16_f32 v128, v128, v129
	s_nop 0
	v_cvt_pk_bf16_f32 v129, v130, v131
	global_store_dwordx2 v[142:143], v[128:129], off offset:288
	ds_bpermute_b32 v128, v182, v132
	s_waitcnt lgkmcnt(0)
	v_add_f32_e32 v128, v132, v128
	ds_bpermute_b32 v129, v183, v128
	s_and_saveexec_b64 s[36:37], s[6:7]
	s_cbranch_execz .LBB0_538
; __device__ __forceinline__ float shx(float v, int o, int lane) { return __int_as_float(__builtin_amdgcn_ds_bpermute((lane ^ o) << 2, __float_as_int(v))); }
;     __device__ __forceinline__ void operator()(const f32x4 (&acc)[2][2][4][2], const Unit& u, int wr, int wc, int fr, int fq) const {
;     ...
;                 ss += shx(ss, 16, lane); ss += shx(ss, 32, lane);
;                 if (fq == 0) scr[(ai * HALF + wr * 64 + m * 16 + fr) * 4 + wc] = ss; }
	s_waitcnt lgkmcnt(0)
	v_add_f32_e32 v128, v128, v129
	ds_write_b32 v184, v128

; __device__ __forceinline__ unsigned cvt_pk_bf16(float lo, float hi) { unsigned r; asm volatile("v_cvt_pk_bf16_f32 %0, %1, %2" : "=v"(r) : "v"(lo), "v"(hi)); return r; }
; __device__ __forceinline__ float shx(float v, int o, int lane) { return __int_as_float(__builtin_amdgcn_ds_bpermute((lane ^ o) << 2, __float_as_int(v))); }
;     __device__ __forceinline__ void operator()(const f32x4 (&acc)[2][2][4][2], const Unit& u, int wr, int wc, int fr, int fq) const {
;         const int bidx = u.pm >> 4, row0 = u.pm * BM + wr * 64 + fr, col0 = u.pn * BM + wc * 32 + 4 * fq, lane = fq * 16 + fr;
;         f32x4 gv[2][2], gs[2][2];
; #pragma unroll
;         for (int bj = 0; bj < 2; ++bj)
; #pragma unroll
;             for (int n = 0; n < 2; ++n) { const int c = col0 + bj * HALF + n * 16; gv[bj][n] = *(const f32x4*)(gate + (size_t)bidx * NMOD + c);
;                 gs[bj][n] = *(const f32x4*)(gnext + c) * (*(const f32x4*)(scn + (size_t)bidx * NMOD + c) + 1.0f); }
; #pragma unroll
;         for (int ai = 0; ai < 2; ++ai)
; #pragma unroll
;             for (int m = 0; m < 4; ++m) { const int row = row0 + ai * HALF + m * 16; const size_t off = (size_t)row * DM + col0; float ss = 0.f;
; #pragma unroll
;                 for (int bj = 0; bj < 2; ++bj)
; #pragma unroll
;                     for (int n = 0; n < 2; ++n) { const f32x4 x = *(const f32x4*)(src + off + bj * HALF + n * 16) + gv[bj][n] * acc[ai][bj][m][n];
;                         *(f32x4*)(dst + off + bj * HALF + n * 16) = x; ss += (x[0] * x[0] + x[1] * x[1]) + (x[2] * x[2] + x[3] * x[3]);
;                         const f32x4 hh = x * gs[bj][n]; u32x2 w; w.x = cvt_pk_bf16(hh[0], hh[1]); w.y = cvt_pk_bf16(hh[2], hh[3]); *(u32x2*)(Hn + off + bj * HALF + n * 16) = w; }
;                 ss += shx(ss, 16, lane); ss += shx(ss, 32, lane);
;                 if (fq == 0) scr[(ai * HALF + wr * 64 + m * 16 + fr) * 4 + wc] = ss; }
.LBB0_1578:
	s_ashr_i32 s25, s34, 4
	s_lshl_b32 s34, s34, 8
	s_mul_hi_i32 s27, s25, 0x6000
	s_mulk_i32 s25, 0x6000
	v_lshl_or_b32 v168, s36, 8, v185
	s_add_u32 s36, s55, s25
	s_addc_u32 s37, s56, s27
	s_add_u32 s38, s57, s25
	v_ashrrev_i32_e32 v169, 31, v168
	s_addc_u32 s39, s58, s27
	v_lshlrev_b64 v[76:77], 2, v[168:169]
	v_lshl_add_u64 v[176:177], s[38:39], 0, v[76:77]
	v_lshl_add_u64 v[170:171], s[36:37], 0, v[76:77]
	v_lshl_add_u64 v[174:175], s[20:21], 0, v[76:77]
	global_load_dwordx4 v[196:199], v[176:177], off
	global_load_dwordx4 v[200:203], v[174:175], off
	global_load_dwordx4 v[204:207], v[170:171], off
	global_load_dwordx4 v[208:211], v[170:171], off offset:64
	global_load_dwordx4 v[212:215], v[174:175], off offset:64
	global_load_dwordx4 v[216:219], v[176:177], off offset:64
	global_load_dwordx4 v[220:223], v[170:171], off offset:512
	global_load_dwordx4 v[224:227], v[174:175], off offset:512
	global_load_dwordx4 v[228:231], v[176:177], off offset:512
	global_load_dwordx4 v[232:235], v[170:171], off offset:576
	global_load_dwordx4 v[236:239], v[174:175], off offset:576
	global_load_dwordx4 v[240:243], v[176:177], off offset:576
	s_waitcnt vmcnt(0)
	v_mov_b32_e32 v76, v196
	v_mov_b32_e32 v77, v197
	v_mov_b32_e32 v78, v198
	v_mov_b32_e32 v79, v199
	v_mov_b32_e32 v72, v200
	v_mov_b32_e32 v73, v201
	v_mov_b32_e32 v74, v202
	v_mov_b32_e32 v75, v203
	v_mov_b32_e32 v88, v204
	v_mov_b32_e32 v89, v205
	v_mov_b32_e32 v90, v206
	v_mov_b32_e32 v91, v207
	v_pk_add_f32 v[78:79], v[78:79], 1.0 op_sel_hi:[1,0]
	v_pk_add_f32 v[76:77], v[76:77], 1.0 op_sel_hi:[1,0]
	v_pk_mul_f32 v[164:165], v[74:75], v[78:79]
	v_pk_mul_f32 v[166:167], v[72:73], v[76:77]
	v_mov_b32_e32 v92, v208
	v_mov_b32_e32 v93, v209
	v_mov_b32_e32 v94, v210
	v_mov_b32_e32 v95, v211
	v_mov_b32_e32 v72, v212
	v_mov_b32_e32 v73, v213
	v_mov_b32_e32 v74, v214
	v_mov_b32_e32 v75, v215
	v_mov_b32_e32 v76, v216
	v_mov_b32_e32 v77, v217
	v_mov_b32_e32 v78, v218
	v_mov_b32_e32 v79, v219
	v_pk_add_f32 v[78:79], v[78:79], 1.0 op_sel_hi:[1,0]
	v_pk_add_f32 v[76:77], v[76:77], 1.0 op_sel_hi:[1,0]
	v_pk_mul_f32 v[160:161], v[74:75], v[78:79]
	v_pk_mul_f32 v[162:163], v[72:73], v[76:77]
	v_mov_b32_e32 v76, v220
	v_mov_b32_e32 v77, v221
	v_mov_b32_e32 v78, v222
	v_mov_b32_e32 v79, v223
	v_mov_b32_e32 v72, v224
	v_mov_b32_e32 v73, v225
	v_mov_b32_e32 v74, v226
	v_mov_b32_e32 v75, v227
	v_mov_b32_e32 v152, v228
	v_mov_b32_e32 v153, v229
	v_mov_b32_e32 v154, v230
	v_mov_b32_e32 v155, v231
	v_pk_add_f32 v[154:155], v[154:155], 1.0 op_sel_hi:[1,0]
	v_pk_add_f32 v[152:153], v[152:153], 1.0 op_sel_hi:[1,0]
	v_pk_mul_f32 v[156:157], v[74:75], v[154:155]
	v_pk_mul_f32 v[158:159], v[72:73], v[152:153]
	v_mov_b32_e32 v72, v232
	v_mov_b32_e32 v73, v233
	v_mov_b32_e32 v74, v234
	v_mov_b32_e32 v75, v235
	v_mov_b32_e32 v152, v236
	v_mov_b32_e32 v153, v237
	v_mov_b32_e32 v154, v238
	v_mov_b32_e32 v155, v239
	s_nop 0
	v_mov_b32_e32 v174, v240
	v_mov_b32_e32 v175, v241
	v_mov_b32_e32 v176, v242
	v_mov_b32_e32 v177, v243
	v_pk_add_f32 v[170:171], v[176:177], 1.0 op_sel_hi:[1,0]
	s_nop 0
	v_pk_mul_f32 v[154:155], v[154:155], v[170:171]
	v_add_u32_e32 v170, s34, v180
	v_pk_add_f32 v[174:175], v[174:175], 1.0 op_sel_hi:[1,0]
	v_ashrrev_i32_e32 v171, 31, v170
	v_pk_mul_f32 v[152:153], v[152:153], v[174:175]
	v_lshlrev_b64 v[174:175], 10, v[170:171]
	v_lshl_add_u64 v[192:193], v[174:175], 0, v[168:169]
	v_lshlrev_b64 v[194:195], 2, v[192:193]
	v_lshl_add_u64 v[178:179], s[4:5], 0, v[194:195]
	v_mov_b32_e32 v228, v194
	v_mov_b32_e32 v229, v228
	global_load_dwordx4 v[196:199], v229, s[4:5]
	global_load_dwordx4 v[200:203], v229, s[4:5] offset:64
	global_load_dwordx4 v[204:207], v229, s[4:5] offset:512
	global_load_dwordx4 v[208:211], v229, s[4:5] offset:576
	v_add_u32_e32 v229, 0x10000, v228
	global_load_dwordx4 v[212:215], v229, s[4:5]
	global_load_dwordx4 v[216:219], v229, s[4:5] offset:64
	global_load_dwordx4 v[220:223], v229, s[4:5] offset:512
	global_load_dwordx4 v[224:227], v229, s[4:5] offset:576
	s_waitcnt vmcnt(7)
	v_pk_fma_f32 v[176:177], v[142:143], v[90:91], v[198:199]
	v_pk_fma_f32 v[174:175], v[140:141], v[88:89], v[196:197]
	v_mul_f32_e32 v143, v177, v177
	v_mul_f32_e32 v142, v175, v175
	v_lshl_add_u64 v[140:141], s[12:13], 0, v[194:195]
	v_fmac_f32_e32 v142, v174, v174
	v_fmac_f32_e32 v143, v176, v176
	global_store_dwordx4 v[140:141], v[174:177], off
	v_add_f32_e32 v194, v142, v143
	v_pk_mul_f32 v[142:143], v[164:165], v[176:177]
	v_pk_mul_f32 v[174:175], v[166:167], v[174:175]
	s_nop 0
	v_cvt_pk_bf16_f32 v174, v174, v175
	v_cvt_pk_bf16_f32 v175, v142, v143
	v_lshl_add_u64 v[142:143], v[192:193], 1, s[18:19]
	global_store_dwordx2 v[142:143], v[174:175], off
	s_waitcnt vmcnt(8)
	v_pk_fma_f32 v[136:137], v[136:137], v[92:93], v[200:201]
	v_pk_fma_f32 v[138:139], v[138:139], v[94:95], v[202:203]
	v_mul_f32_e32 v174, v137, v137
	global_store_dwordx4 v[140:141], v[136:139], off offset:64
	v_fmac_f32_e32 v174, v136, v136
	v_mul_f32_e32 v175, v139, v139
	v_pk_mul_f32 v[136:137], v[162:163], v[136:137]
	v_fmac_f32_e32 v175, v138, v138
	v_pk_mul_f32 v[138:139], v[160:161], v[138:139]
	v_cvt_pk_bf16_f32 v136, v136, v137
	v_add_f32_e32 v174, v174, v175
	v_cvt_pk_bf16_f32 v137, v138, v139
	global_store_dwordx2 v[142:143], v[136:137], off offset:32
	v_add_f32_e32 v174, v194, v174
	s_waitcnt vmcnt(9)
	v_pk_fma_f32 v[132:133], v[132:133], v[76:77], v[204:205]
	v_pk_fma_f32 v[134:135], v[134:135], v[78:79], v[206:207]
	v_mul_f32_e32 v136, v133, v133
	global_store_dwordx4 v[140:141], v[132:135], off offset:512
	v_fmac_f32_e32 v136, v132, v132
	v_mul_f32_e32 v137, v135, v135
	v_pk_mul_f32 v[132:133], v[158:159], v[132:133]
	v_fmac_f32_e32 v137, v134, v134
	v_pk_mul_f32 v[134:135], v[156:157], v[134:135]
	v_cvt_pk_bf16_f32 v132, v132, v133
	v_add_f32_e32 v136, v136, v137
	v_cvt_pk_bf16_f32 v133, v134, v135
	global_store_dwordx2 v[142:143], v[132:133], off offset:256
	v_add_f32_e32 v136, v174, v136
	s_waitcnt vmcnt(10)
	v_pk_fma_f32 v[130:131], v[130:131], v[74:75], v[210:211]
	v_pk_fma_f32 v[128:129], v[128:129], v[72:73], v[208:209]
	v_add_u32_e32 v229, 0x20000, v228
	global_load_dwordx4 v[196:199], v229, s[4:5]
	global_load_dwordx4 v[200:203], v229, s[4:5] offset:64
	global_load_dwordx4 v[204:207], v229, s[4:5] offset:512
	global_load_dwordx4 v[208:211], v229, s[4:5] offset:576
	v_mul_f32_e32 v133, v131, v131
	v_mul_f32_e32 v132, v129, v129
	v_fmac_f32_e32 v132, v128, v128
	v_fmac_f32_e32 v133, v130, v130
	global_store_dwordx4 v[140:141], v[128:131], off offset:576
	v_add_f32_e32 v132, v132, v133
	v_add_f32_e32 v132, v136, v132
	v_pk_mul_f32 v[128:129], v[152:153], v[128:129]
	v_pk_mul_f32 v[130:131], v[154:155], v[130:131]
	v_cvt_pk_bf16_f32 v128, v128, v129
	s_nop 0
	v_cvt_pk_bf16_f32 v129, v130, v131
	global_store_dwordx2 v[142:143], v[128:129], off offset:288
	ds_bpermute_b32 v128, v182, v132
	s_waitcnt lgkmcnt(0)
	v_add_f32_e32 v128, v132, v128
	ds_bpermute_b32 v129, v183, v128
	s_and_saveexec_b64 s[36:37], s[6:7]
	s_cbranch_execz .LBB0_1580
; __device__ __forceinline__ float shx(float v, int o, int lane) { return __int_as_float(__builtin_amdgcn_ds_bpermute((lane ^ o) << 2, __float_as_int(v))); }
;     __device__ __forceinline__ void operator()(const f32x4 (&acc)[2][2][4][2], const Unit& u, int wr, int wc, int fr, int fq) const {
;     ...
;                 ss += shx(ss, 16, lane); ss += shx(ss, 32, lane);
;                 if (fq == 0) scr[(ai * HALF + wr * 64 + m * 16 + fr) * 4 + wc] = ss; }
	s_waitcnt lgkmcnt(0)
	v_add_f32_e32 v128, v128, v129
	ds_write_b32 v184, v128

; __device__ __forceinline__ unsigned cvt_pk_bf16(float lo, float hi) { unsigned r; asm volatile("v_cvt_pk_bf16_f32 %0, %1, %2" : "=v"(r) : "v"(lo), "v"(hi)); return r; }
; __device__ __forceinline__ float shx(float v, int o, int lane) { return __int_as_float(__builtin_amdgcn_ds_bpermute((lane ^ o) << 2, __float_as_int(v))); }
;     __device__ __forceinline__ void operator()(const f32x4 (&acc)[2][2][4][2], const Unit& u, int wr, int wc, int fr, int fq) const {
;         const int bidx = u.pm >> 4, row0 = u.pm * BM + wr * 64 + fr, col0 = u.pn * BM + wc * 32 + 4 * fq, lane = fq * 16 + fr;
;         f32x4 gv[2][2], gs[2][2];
; #pragma unroll
;         for (int bj = 0; bj < 2; ++bj)
; #pragma unroll
;             for (int n = 0; n < 2; ++n) { const int c = col0 + bj * HALF + n * 16; gv[bj][n] = *(const f32x4*)(gate + (size_t)bidx * NMOD + c);
;                 gs[bj][n] = *(const f32x4*)(gnext + c) * (*(const f32x4*)(scn + (size_t)bidx * NMOD + c) + 1.0f); }
; #pragma unroll
;         for (int ai = 0; ai < 2; ++ai)
; #pragma unroll
;             for (int m = 0; m < 4; ++m) { const int row = row0 + ai * HALF + m * 16; const size_t off = (size_t)row * DM + col0; float ss = 0.f;
; #pragma unroll
;                 for (int bj = 0; bj < 2; ++bj)
; #pragma unroll
;                     for (int n = 0; n < 2; ++n) { const f32x4 x = *(const f32x4*)(src + off + bj * HALF + n * 16) + gv[bj][n] * acc[ai][bj][m][n];
;                         *(f32x4*)(dst + off + bj * HALF + n * 16) = x; ss += (x[0] * x[0] + x[1] * x[1]) + (x[2] * x[2] + x[3] * x[3]);
;                         const f32x4 hh = x * gs[bj][n]; u32x2 w; w.x = cvt_pk_bf16(hh[0], hh[1]); w.y = cvt_pk_bf16(hh[2], hh[3]); *(u32x2*)(Hn + off + bj * HALF + n * 16) = w; }
;                 ss += shx(ss, 16, lane); ss += shx(ss, 32, lane);
;                 if (fq == 0) scr[(ai * HALF + wr * 64 + m * 16 + fr) * 4 + wc] = ss; }
.LBB0_1909:
	s_ashr_i32 s25, s34, 4
	s_lshl_b32 s34, s34, 8
	s_mul_hi_i32 s27, s25, 0x6000
	s_mulk_i32 s25, 0x6000
	v_lshl_or_b32 v168, s36, 8, v185
	s_add_u32 s36, s58, s25
	s_addc_u32 s37, s59, s27
	s_add_u32 s38, s60, s25
	v_ashrrev_i32_e32 v169, 31, v168
	s_addc_u32 s39, s61, s27
	v_lshlrev_b64 v[80:81], 2, v[168:169]
	v_lshl_add_u64 v[176:177], s[38:39], 0, v[80:81]
	v_lshl_add_u64 v[170:171], s[36:37], 0, v[80:81]
	v_lshl_add_u64 v[174:175], s[20:21], 0, v[80:81]
	global_load_dwordx4 v[196:199], v[176:177], off
	global_load_dwordx4 v[200:203], v[174:175], off
	global_load_dwordx4 v[204:207], v[170:171], off
	global_load_dwordx4 v[208:211], v[170:171], off offset:64
	global_load_dwordx4 v[212:215], v[174:175], off offset:64
	global_load_dwordx4 v[216:219], v[176:177], off offset:64
	global_load_dwordx4 v[220:223], v[170:171], off offset:512
	global_load_dwordx4 v[224:227], v[174:175], off offset:512
	global_load_dwordx4 v[228:231], v[176:177], off offset:512
	global_load_dwordx4 v[232:235], v[170:171], off offset:576
	global_load_dwordx4 v[236:239], v[174:175], off offset:576
	global_load_dwordx4 v[240:243], v[176:177], off offset:576
	s_waitcnt vmcnt(0)
	v_mov_b32_e32 v80, v196
	v_mov_b32_e32 v81, v197
	v_mov_b32_e32 v82, v198
	v_mov_b32_e32 v83, v199
	v_mov_b32_e32 v72, v200
	v_mov_b32_e32 v73, v201
	v_mov_b32_e32 v74, v202
	v_mov_b32_e32 v75, v203
	v_mov_b32_e32 v92, v204
	v_mov_b32_e32 v93, v205
	v_mov_b32_e32 v94, v206
	v_mov_b32_e32 v95, v207
	v_pk_add_f32 v[82:83], v[82:83], 1.0 op_sel_hi:[1,0]
	v_pk_add_f32 v[80:81], v[80:81], 1.0 op_sel_hi:[1,0]
	v_pk_mul_f32 v[164:165], v[74:75], v[82:83]
	v_pk_mul_f32 v[166:167], v[72:73], v[80:81]
	v_mov_b32_e32 v88, v208
	v_mov_b32_e32 v89, v209
	v_mov_b32_e32 v90, v210
	v_mov_b32_e32 v91, v211
	v_mov_b32_e32 v72, v212
	v_mov_b32_e32 v73, v213
	v_mov_b32_e32 v74, v214
	v_mov_b32_e32 v75, v215
	v_mov_b32_e32 v80, v216
	v_mov_b32_e32 v81, v217
	v_mov_b32_e32 v82, v218
	v_mov_b32_e32 v83, v219
	v_pk_add_f32 v[82:83], v[82:83], 1.0 op_sel_hi:[1,0]
	v_pk_add_f32 v[80:81], v[80:81], 1.0 op_sel_hi:[1,0]
	v_pk_mul_f32 v[160:161], v[74:75], v[82:83]
	v_pk_mul_f32 v[162:163], v[72:73], v[80:81]
	v_mov_b32_e32 v80, v220
	v_mov_b32_e32 v81, v221
	v_mov_b32_e32 v82, v222
	v_mov_b32_e32 v83, v223
	v_mov_b32_e32 v72, v224
	v_mov_b32_e32 v73, v225
	v_mov_b32_e32 v74, v226
	v_mov_b32_e32 v75, v227
	v_mov_b32_e32 v152, v228
	v_mov_b32_e32 v153, v229
	v_mov_b32_e32 v154, v230
	v_mov_b32_e32 v155, v231
	v_pk_add_f32 v[154:155], v[154:155], 1.0 op_sel_hi:[1,0]
	v_pk_add_f32 v[152:153], v[152:153], 1.0 op_sel_hi:[1,0]
	v_pk_mul_f32 v[156:157], v[74:75], v[154:155]
	v_pk_mul_f32 v[158:159], v[72:73], v[152:153]
	v_mov_b32_e32 v72, v232
	v_mov_b32_e32 v73, v233
	v_mov_b32_e32 v74, v234
	v_mov_b32_e32 v75, v235
	v_mov_b32_e32 v152, v236
	v_mov_b32_e32 v153, v237
	v_mov_b32_e32 v154, v238
	v_mov_b32_e32 v155, v239
	s_nop 0
	v_mov_b32_e32 v174, v240
	v_mov_b32_e32 v175, v241
	v_mov_b32_e32 v176, v242
	v_mov_b32_e32 v177, v243
	v_pk_add_f32 v[170:171], v[176:177], 1.0 op_sel_hi:[1,0]
	s_nop 0
	v_pk_mul_f32 v[154:155], v[154:155], v[170:171]
	v_add_u32_e32 v170, s34, v180
	v_pk_add_f32 v[174:175], v[174:175], 1.0 op_sel_hi:[1,0]
	v_ashrrev_i32_e32 v171, 31, v170
	v_pk_mul_f32 v[152:153], v[152:153], v[174:175]
	v_lshlrev_b64 v[174:175], 10, v[170:171]
	v_lshl_add_u64 v[192:193], v[174:175], 0, v[168:169]
	v_lshl_add_u64 v[178:179], v[192:193], 2, s[16:17]
	v_lshlrev_b32_e32 v228, 2, v192
	v_mov_b32_e32 v229, v228
	global_load_dwordx4 v[196:199], v229, s[16:17]
	global_load_dwordx4 v[200:203], v229, s[16:17] offset:64
	global_load_dwordx4 v[204:207], v229, s[16:17] offset:512
	global_load_dwordx4 v[208:211], v229, s[16:17] offset:576
	v_add_u32_e32 v229, 0x10000, v228
	global_load_dwordx4 v[212:215], v229, s[16:17]
	global_load_dwordx4 v[216:219], v229, s[16:17] offset:64
	global_load_dwordx4 v[220:223], v229, s[16:17] offset:512
	global_load_dwordx4 v[224:227], v229, s[16:17] offset:576
	s_waitcnt vmcnt(7)
	v_pk_fma_f32 v[142:143], v[142:143], v[94:95], v[198:199]
	v_pk_fma_f32 v[140:141], v[140:141], v[92:93], v[196:197]
	v_mul_f32_e32 v175, v143, v143
	v_mul_f32_e32 v174, v141, v141
	global_store_dwordx4 v[178:179], v[140:143], off
	v_fmac_f32_e32 v174, v140, v140
	v_fmac_f32_e32 v175, v142, v142
	v_pk_mul_f32 v[140:141], v[166:167], v[140:141]
	v_add_f32_e32 v194, v174, v175
	v_cvt_pk_bf16_f32 v174, v140, v141
	v_lshl_add_u64 v[140:141], v[192:193], 1, s[14:15]
	v_pk_mul_f32 v[142:143], v[164:165], v[142:143]
	s_nop 0
	v_cvt_pk_bf16_f32 v175, v142, v143
	global_store_dwordx2 v[140:141], v[174:175], off
	s_waitcnt vmcnt(8)
	v_pk_fma_f32 v[136:137], v[136:137], v[88:89], v[200:201]
	v_pk_fma_f32 v[138:139], v[138:139], v[90:91], v[202:203]
	v_mul_f32_e32 v142, v137, v137
	global_store_dwordx4 v[178:179], v[136:139], off offset:64
	v_fmac_f32_e32 v142, v136, v136
	v_mul_f32_e32 v143, v139, v139
	v_pk_mul_f32 v[136:137], v[162:163], v[136:137]
	v_fmac_f32_e32 v143, v138, v138
	v_pk_mul_f32 v[138:139], v[160:161], v[138:139]
	v_cvt_pk_bf16_f32 v136, v136, v137
	v_add_f32_e32 v142, v142, v143
	v_cvt_pk_bf16_f32 v137, v138, v139
	global_store_dwordx2 v[140:141], v[136:137], off offset:32
	v_add_f32_e32 v142, v194, v142
	s_waitcnt vmcnt(9)
	v_pk_fma_f32 v[132:133], v[132:133], v[80:81], v[204:205]
	v_pk_fma_f32 v[134:135], v[134:135], v[82:83], v[206:207]
	v_mul_f32_e32 v136, v133, v133
	global_store_dwordx4 v[178:179], v[132:135], off offset:512
	v_fmac_f32_e32 v136, v132, v132
	v_mul_f32_e32 v137, v135, v135
	v_pk_mul_f32 v[132:133], v[158:159], v[132:133]
	v_fmac_f32_e32 v137, v134, v134
	v_pk_mul_f32 v[134:135], v[156:157], v[134:135]
	v_cvt_pk_bf16_f32 v132, v132, v133
	v_add_f32_e32 v136, v136, v137
	v_cvt_pk_bf16_f32 v133, v134, v135
	global_store_dwordx2 v[140:141], v[132:133], off offset:256
	v_add_f32_e32 v136, v142, v136
	s_waitcnt vmcnt(10)
	v_pk_fma_f32 v[130:131], v[130:131], v[74:75], v[210:211]
	v_pk_fma_f32 v[128:129], v[128:129], v[72:73], v[208:209]
	v_add_u32_e32 v229, 0x20000, v228
	global_load_dwordx4 v[196:199], v229, s[16:17]
	global_load_dwordx4 v[200:203], v229, s[16:17] offset:64
	global_load_dwordx4 v[204:207], v229, s[16:17] offset:512
	global_load_dwordx4 v[208:211], v229, s[16:17] offset:576
	v_mul_f32_e32 v133, v131, v131
	v_mul_f32_e32 v132, v129, v129
	v_fmac_f32_e32 v132, v128, v128
	v_fmac_f32_e32 v133, v130, v130
	global_store_dwordx4 v[178:179], v[128:131], off offset:576
	v_add_f32_e32 v132, v132, v133
	v_add_f32_e32 v132, v136, v132
	v_pk_mul_f32 v[128:129], v[152:153], v[128:129]
	v_pk_mul_f32 v[130:131], v[154:155], v[130:131]
	v_cvt_pk_bf16_f32 v128, v128, v129
	s_nop 0
	v_cvt_pk_bf16_f32 v129, v130, v131
	global_store_dwordx2 v[140:141], v[128:129], off offset:288
	ds_bpermute_b32 v128, v182, v132
	s_waitcnt lgkmcnt(0)
	v_add_f32_e32 v128, v132, v128
	ds_bpermute_b32 v129, v183, v128
	s_and_saveexec_b64 s[36:37], s[8:9]
	s_mov_b32 s70, 0xbf3a00e3
	s_cbranch_execz .LBB0_1911
	s_waitcnt lgkmcnt(0)
	v_add_f32_e32 v128, v128, v129
	ds_write_b32 v184, v128
